# code placement: conv tile loop, swiglu epilogue entry and final_norm loop heads also 64-byte aligned
# speedup vs baseline: 1.0008x; 1.0008x over previous
.Lpeelx_357:
	s_mov_b32 s56, s61
	.p2align	6

.LBB7_803:
	s_or_b64 exec, exec, s[6:7]
	v_readlane_b32 s4, v252, 7
	v_readlane_b32 s5, v252, 8
	s_andn2_b64 vcc, exec, s[4:5]
	s_cbranch_vccnz .LBB7_813
	s_load_dwordx8 s[12:19], s[42:43], 0xa0
	v_readlane_b32 s4, v250, 10
	v_readlane_b32 s5, v250, 11
	s_lshl_b64 s[4:5], s[4:5], 2
	v_readlane_b32 s3, v250, 27
	s_waitcnt lgkmcnt(0)
	s_add_u32 s6, s18, s4
	s_addc_u32 s7, s19, s5
	s_add_u32 s8, s16, s4
	s_addc_u32 s9, s17, s5
	s_add_u32 s12, s12, s3
	s_movk_i32 s3, 0xba0
	s_addc_u32 s13, s13, 0
	v_cmp_gt_i32_e32 vcc, s3, v150
	s_movk_i32 s3, 0x180
	s_add_u32 s4, s14, s4
	v_cmp_gt_i32_e64 s[40:41], s3, v150
	v_ashrrev_i32_e32 v151, 31, v150
	v_lshlrev_b32_e32 v0, 2, v150
	v_readlane_b32 s3, v253, 39
	s_addc_u32 s5, s15, s5
	v_lshlrev_b64 v[2:3], 2, v[150:151]
	v_add_u32_e32 v108, 0, v0
	v_add_u32_e32 v109, s3, v0
	v_mov_b32_e32 v0, s3
	v_lshl_add_u64 v[10:11], s[4:5], 0, v[2:3]
	v_mad_u64_u32 v[12:13], s[4:5], v204, 24, v[0:1]
	v_lshl_add_u64 v[14:15], s[12:13], 0, v[2:3]
	s_mov_b64 s[4:5], 0x1200
	v_lshl_add_u64 v[16:17], v[14:15], 0, s[4:5]
	s_mov_b64 s[4:5], 0x1800
	v_lshl_add_u64 v[18:19], v[14:15], 0, s[4:5]
	s_mov_b64 s[4:5], 0x1e00
	v_lshl_add_u64 v[20:21], v[14:15], 0, s[4:5]
	s_mov_b64 s[4:5], 0x2400
	v_lshl_add_u64 v[22:23], v[14:15], 0, s[4:5]
	s_mov_b64 s[4:5], 0x2a00
	v_lshl_add_u64 v[24:25], v[14:15], 0, s[4:5]
	s_mov_b64 s[4:5], 0x3000
	v_lshl_add_u64 v[26:27], v[14:15], 0, s[4:5]
	s_mov_b64 s[4:5], 0x3600
	v_and_b32_e32 v0, 64, v163
	v_lshl_add_u64 v[28:29], v[14:15], 0, s[4:5]
	s_mov_b64 s[4:5], 0x3c00
	v_add_u32_e32 v0, 64, v0
	v_xor_b32_e32 v4, 1, v163
	v_lshl_add_u64 v[30:31], v[14:15], 0, s[4:5]
	s_mov_b64 s[4:5], 0x4200
	v_cmp_lt_i32_e64 s[42:43], v4, v0
	v_lshl_add_u64 v[32:33], v[14:15], 0, s[4:5]
	s_mov_b64 s[4:5], 0x4800
	v_cndmask_b32_e64 v4, v163, v4, s[42:43]
	v_lshl_add_u64 v[34:35], v[14:15], 0, s[4:5]
	s_mov_b64 s[4:5], 0x4e00
	v_lshlrev_b32_e32 v13, 2, v4
	v_xor_b32_e32 v4, 2, v163
	v_lshl_add_u64 v[36:37], v[14:15], 0, s[4:5]
	s_mov_b64 s[4:5], 0x5400
	v_cmp_lt_i32_e64 s[42:43], v4, v0
	v_lshl_add_u64 v[38:39], v[14:15], 0, s[4:5]
	s_mov_b64 s[4:5], 0x5a00
	v_cndmask_b32_e64 v4, v163, v4, s[42:43]
	v_lshl_add_u64 v[40:41], v[14:15], 0, s[4:5]
	s_mov_b64 s[4:5], 0x6000
	v_lshlrev_b32_e32 v110, 2, v4
	v_xor_b32_e32 v4, 4, v163
	v_lshl_add_u64 v[42:43], v[14:15], 0, s[4:5]
	s_mov_b64 s[4:5], 0x6600
	v_cmp_lt_i32_e64 s[42:43], v4, v0
	v_lshl_add_u64 v[44:45], v[14:15], 0, s[4:5]
	s_mov_b64 s[4:5], 0x6c00
	v_cndmask_b32_e64 v4, v163, v4, s[42:43]
	v_lshl_add_u64 v[46:47], v[14:15], 0, s[4:5]
	s_mov_b64 s[4:5], 0x7200
	v_lshlrev_b32_e32 v111, 2, v4
	v_xor_b32_e32 v4, 8, v163
	v_lshl_add_u64 v[48:49], v[14:15], 0, s[4:5]
	s_mov_b64 s[4:5], 0x7800
	v_cmp_lt_i32_e64 s[42:43], v4, v0
	v_lshl_add_u64 v[50:51], v[14:15], 0, s[4:5]
	s_mov_b64 s[4:5], 0x7e00
	v_cndmask_b32_e64 v4, v163, v4, s[42:43]
	v_lshl_add_u64 v[52:53], v[14:15], 0, s[4:5]
	s_mov_b64 s[4:5], 0x8400
	v_lshlrev_b32_e32 v112, 2, v4
	v_xor_b32_e32 v4, 16, v163
	v_lshl_add_u64 v[54:55], v[14:15], 0, s[4:5]
	s_mov_b64 s[4:5], 0x8a00
	v_cmp_lt_i32_e64 s[42:43], v4, v0
	v_lshl_add_u64 v[56:57], v[14:15], 0, s[4:5]
	s_mov_b64 s[4:5], 0x9000
	v_cndmask_b32_e64 v4, v163, v4, s[42:43]
	v_lshl_add_u64 v[58:59], v[14:15], 0, s[4:5]
	s_mov_b64 s[4:5], 0x9600
	v_lshlrev_b32_e32 v113, 2, v4
	v_xor_b32_e32 v4, 32, v163
	v_lshl_add_u64 v[60:61], v[14:15], 0, s[4:5]
	s_mov_b64 s[4:5], 0x9c00
	v_cmp_lt_i32_e64 s[42:43], v4, v0
	v_lshl_add_u64 v[62:63], v[14:15], 0, s[4:5]
	s_mov_b64 s[4:5], 0xa200
	v_cndmask_b32_e64 v0, v163, v4, s[42:43]
	v_mul_lo_u32 v4, v204, 6
	v_lshl_add_u64 v[64:65], v[14:15], 0, s[4:5]
	s_mov_b64 s[4:5], 0xa800
	v_ashrrev_i32_e32 v5, 31, v4
	v_lshl_add_u64 v[66:67], v[14:15], 0, s[4:5]
	s_mov_b64 s[4:5], 0xae00
	v_lshl_add_u64 v[68:69], v[14:15], 0, s[4:5]
	s_mov_b64 s[4:5], 0xb400
	v_lshlrev_b64 v[2:3], 2, v[4:5]
	v_lshlrev_b32_e32 v114, 2, v0
	v_lshl_add_u64 v[70:71], v[14:15], 0, s[4:5]
	v_add_u32_e32 v115, 0x10200, v108
	v_add_u32_e32 v116, 0x10800, v108
	v_add_u32_e32 v117, 0x10e00, v108
	v_add_u32_e32 v118, 0x11400, v108
	v_add_u32_e32 v119, 0x11a00, v108
	v_add_u32_e32 v120, 0x12000, v108
	v_add_u32_e32 v121, 0x12600, v108
	v_add_u32_e32 v122, 0x12c00, v108
	v_add_u32_e32 v123, 0x13200, v108
	v_add_u32_e32 v124, 0x13800, v108
	v_add_u32_e32 v125, 0x13e00, v108
	v_add_u32_e32 v126, 0x14400, v108
	v_add_u32_e32 v127, 0x14a00, v108
	v_add_u32_e32 v128, 0x15000, v108
	v_add_u32_e32 v129, 0x15600, v108
	v_add_u32_e32 v130, 0x15c00, v108
	v_add_u32_e32 v131, 0x16200, v108
	v_add_u32_e32 v132, 0x16800, v108
	v_add_u32_e32 v133, 0x16e00, v108
	v_lshl_add_u64 v[72:73], s[8:9], 0, v[2:3]
	v_lshl_add_u64 v[74:75], s[6:7], 0, v[2:3]
	v_lshl_add_u64 v[76:77], v[4:5], 1, s[0:1]
	s_and_saveexec_b64 s[4:5], s[40:41]
	global_load_dword v247, v[10:11], off
	global_load_dword v216, v[14:15], off
	global_load_dword v217, v[14:15], off offset:1536
	global_load_dword v218, v[14:15], off offset:3072
	global_load_dword v219, v[16:17], off
	global_load_dword v220, v[18:19], off
	global_load_dword v221, v[20:21], off
	global_load_dword v222, v[22:23], off
	global_load_dword v223, v[24:25], off
	global_load_dword v224, v[26:27], off
	global_load_dword v225, v[28:29], off
	global_load_dword v226, v[30:31], off
	global_load_dword v227, v[32:33], off
	global_load_dword v228, v[34:35], off
	global_load_dword v229, v[36:37], off
	global_load_dword v230, v[38:39], off
	global_load_dword v231, v[40:41], off
	global_load_dword v232, v[42:43], off
	global_load_dword v233, v[44:45], off
	global_load_dword v234, v[46:47], off
	global_load_dword v235, v[48:49], off
	global_load_dword v236, v[50:51], off
	global_load_dword v237, v[52:53], off
	global_load_dword v238, v[54:55], off
	global_load_dword v239, v[56:57], off
	global_load_dword v240, v[58:59], off
	global_load_dword v241, v[60:61], off
	global_load_dword v242, v[62:63], off
	global_load_dword v243, v[64:65], off
	global_load_dword v244, v[66:67], off
	global_load_dword v245, v[68:69], off
	global_load_dword v246, v[70:71], off
	s_or_b64 exec, exec, s[4:5]
	global_load_dwordx4 v[14:17], v[72:73], off
	global_load_dwordx2 v[18:19], v[72:73], off offset:16
	global_load_dwordx4 v[20:23], v[74:75], off
	global_load_dwordx2 v[10:11], v[74:75], off offset:16
	s_mov_b32 s12, s2
	s_movk_i32 s14, 0x1a0
	v_cmp_gt_i32_e64 s[6:7], s14, v150
	s_lshl_b32 s15, s12, 5
	s_and_b32 s3, s15, 0x7e0
	s_sub_i32 s3, 29, s3
	s_sub_i32 s4, s15, 30
	s_mov_b32 s5, 0x2aaaaaab
	s_movk_i32 s14, 0xfe80
	v_mov_b32_e32 v79, v150
	v_mul_hi_i32 v80, v79, s5
	v_lshrrev_b32_e32 v81, 31, v80
	v_ashrrev_i32_e32 v80, 3, v80
	v_add_u32_e32 v80, v80, v81
	v_cmp_lt_i32_e64 s[42:43], s3, v80
	s_nop 1
	s_and_saveexec_b64 s[8:9], s[42:43]
	v_add_u32_e32 v82, s4, v80
	v_ashrrev_i32_e32 v83, 31, v82
	v_lshlrev_b64 v[82:83], 11, v[82:83]
	v_lshl_add_u64 v[82:83], s[44:45], 0, v[82:83]
	v_lshlrev_b32_e32 v84, 3, v79
	v_mad_i32_i24 v84, v80, s14, v84
	v_mov_b32_e32 v85, 0
	v_lshl_add_u64 v[82:83], v[84:85], 1, v[82:83]
	global_load_dwordx4 v[24:27], v[82:83], off offset:512
	global_load_dwordx4 v[28:31], v[82:83], off offset:1280
	s_or_b64 exec, exec, s[8:9]
	v_add_u32_e32 v79, 512, v150
	v_mul_hi_i32 v80, v79, s5
	v_lshrrev_b32_e32 v81, 31, v80
	v_ashrrev_i32_e32 v80, 3, v80
	v_add_u32_e32 v80, v80, v81
	v_cmp_lt_i32_e64 s[42:43], s3, v80
	s_nop 1
	s_and_saveexec_b64 s[8:9], s[42:43]
	v_add_u32_e32 v82, s4, v80
	v_ashrrev_i32_e32 v83, 31, v82
	v_lshlrev_b64 v[82:83], 11, v[82:83]
	v_lshl_add_u64 v[82:83], s[44:45], 0, v[82:83]
	v_lshlrev_b32_e32 v84, 3, v79
	v_mad_i32_i24 v84, v80, s14, v84
	v_mov_b32_e32 v85, 0
	v_lshl_add_u64 v[82:83], v[84:85], 1, v[82:83]
	global_load_dwordx4 v[32:35], v[82:83], off offset:512
	global_load_dwordx4 v[36:39], v[82:83], off offset:1280
	s_or_b64 exec, exec, s[8:9]
	v_add_u32_e32 v79, 1024, v150
	v_mul_hi_i32 v80, v79, s5
	v_lshrrev_b32_e32 v81, 31, v80
	v_ashrrev_i32_e32 v80, 3, v80
	v_add_u32_e32 v80, v80, v81
	v_cmp_lt_i32_e64 s[42:43], s3, v80
	s_nop 1
	s_and_saveexec_b64 s[8:9], s[42:43]
	v_add_u32_e32 v82, s4, v80
	v_ashrrev_i32_e32 v83, 31, v82
	v_lshlrev_b64 v[82:83], 11, v[82:83]
	v_lshl_add_u64 v[82:83], s[44:45], 0, v[82:83]
	v_lshlrev_b32_e32 v84, 3, v79
	v_mad_i32_i24 v84, v80, s14, v84
	v_mov_b32_e32 v85, 0
	v_lshl_add_u64 v[82:83], v[84:85], 1, v[82:83]
	global_load_dwordx4 v[40:43], v[82:83], off offset:512
	global_load_dwordx4 v[44:47], v[82:83], off offset:1280
	s_or_b64 exec, exec, s[8:9]
	v_add_u32_e32 v79, 1536, v150
	v_mul_hi_i32 v80, v79, s5
	v_lshrrev_b32_e32 v81, 31, v80
	v_ashrrev_i32_e32 v80, 3, v80
	v_add_u32_e32 v80, v80, v81
	v_cmp_lt_i32_e64 s[42:43], s3, v80
	s_nop 1
	s_and_saveexec_b64 s[8:9], s[42:43]
	v_add_u32_e32 v82, s4, v80
	v_ashrrev_i32_e32 v83, 31, v82
	v_lshlrev_b64 v[82:83], 11, v[82:83]
	v_lshl_add_u64 v[82:83], s[44:45], 0, v[82:83]
	v_lshlrev_b32_e32 v84, 3, v79
	v_mad_i32_i24 v84, v80, s14, v84
	v_mov_b32_e32 v85, 0
	v_lshl_add_u64 v[82:83], v[84:85], 1, v[82:83]
	global_load_dwordx4 v[48:51], v[82:83], off offset:512
	global_load_dwordx4 v[52:55], v[82:83], off offset:1280
	s_or_b64 exec, exec, s[8:9]
	v_add_u32_e32 v79, 2048, v150
	v_mul_hi_i32 v80, v79, s5
	v_lshrrev_b32_e32 v81, 31, v80
	v_ashrrev_i32_e32 v80, 3, v80
	v_add_u32_e32 v80, v80, v81
	v_cmp_lt_i32_e64 s[42:43], s3, v80
	s_nop 1
	s_and_saveexec_b64 s[8:9], s[42:43]
	v_add_u32_e32 v82, s4, v80
	v_ashrrev_i32_e32 v83, 31, v82
	v_lshlrev_b64 v[82:83], 11, v[82:83]
	v_lshl_add_u64 v[82:83], s[44:45], 0, v[82:83]
	v_lshlrev_b32_e32 v84, 3, v79
	v_mad_i32_i24 v84, v80, s14, v84
	v_mov_b32_e32 v85, 0
	v_lshl_add_u64 v[82:83], v[84:85], 1, v[82:83]
	global_load_dwordx4 v[56:59], v[82:83], off offset:512
	global_load_dwordx4 v[60:63], v[82:83], off offset:1280
	s_or_b64 exec, exec, s[8:9]
	v_add_u32_e32 v79, 2560, v150
	v_mul_hi_i32 v80, v79, s5
	v_lshrrev_b32_e32 v81, 31, v80
	v_ashrrev_i32_e32 v80, 3, v80
	v_add_u32_e32 v80, v80, v81
	v_cmp_lt_i32_e64 s[42:43], s3, v80
	s_nop 1
	s_and_b64 s[42:43], s[42:43], s[6:7]
	s_and_saveexec_b64 s[8:9], s[42:43]
	v_add_u32_e32 v82, s4, v80
	v_ashrrev_i32_e32 v83, 31, v82
	v_lshlrev_b64 v[82:83], 11, v[82:83]
	v_lshl_add_u64 v[82:83], s[44:45], 0, v[82:83]
	v_lshlrev_b32_e32 v84, 3, v79
	v_mad_i32_i24 v84, v80, s14, v84
	v_mov_b32_e32 v85, 0
	v_lshl_add_u64 v[82:83], v[84:85], 1, v[82:83]
	global_load_dwordx4 v[64:67], v[82:83], off offset:512
	global_load_dwordx4 v[68:71], v[82:83], off offset:1280
	s_or_b64 exec, exec, s[8:9]
	s_branch .LBB7_806
	.p2align	6
.LBB7_805:
	s_or_b64 exec, exec, s[0:1]
	v_add_u32_e32 v0, s31, v12
	s_waitcnt lgkmcnt(0)
	s_barrier
	ds_read2_b64 v[2:5], v0 offset1:1
	s_add_i32 s0, s13, s86
	s_ashr_i32 s1, s0, 31
	s_lshl_b64 s[0:1], s[0:1], 11
	s_add_i32 s12, s12, s60
	s_waitcnt lgkmcnt(0)
	v_add_f32_e32 v6, 0, v2
	v_add_f32_e32 v8, v6, v3
	ds_read_b64 v[6:7], v0 offset:16
	v_add_f32_e32 v0, v8, v4
	v_add_f32_e32 v0, v0, v5
	s_waitcnt lgkmcnt(0)
	v_add_f32_e32 v0, v0, v6
	v_add_f32_e32 v0, v0, v7
	s_nop 0
	s_waitcnt lgkmcnt(0)
	s_nop 1
	v_add_f32_dpp v0, v0, v0 quad_perm:[1,0,3,2] row_mask:0xf bank_mask:0xf
	s_nop 0
	s_waitcnt lgkmcnt(0)
	s_nop 1
	v_add_f32_dpp v0, v0, v0 quad_perm:[2,3,0,1] row_mask:0xf bank_mask:0xf
	s_nop 0
	s_waitcnt lgkmcnt(0)
	s_nop 1
	v_add_f32_dpp v0, v0, v0 row_half_mirror row_mask:0xf bank_mask:0xf
	s_nop 0
	s_waitcnt lgkmcnt(0)
	s_nop 1
	v_add_f32_dpp v0, v0, v0 row_mirror row_mask:0xf bank_mask:0xf
	v_mov_b32_e32 v8, v0
	s_nop 1
	v_permlane16_swap_b32_e32 v0, v8
	s_waitcnt lgkmcnt(0)
	v_add_f32_e32 v0, v0, v8
	v_mov_b32_e32 v8, v0
	s_nop 1
	v_permlane32_swap_b32_e32 v0, v8
	s_waitcnt lgkmcnt(0)
	v_add_f32_e32 v8, v0, v8
	v_mul_f32_e32 v0, 0x3b2aaaab, v8
	v_fmac_f32_e32 v3, 0xbb2aaaab, v8
	v_fmamk_f32 v2, v8, 0xbb2aaaab, v2
	v_mul_f32_e32 v78, v3, v3
	v_pk_add_f32 v[8:9], v[4:5], v[0:1] op_sel_hi:[1,0] neg_lo:[0,1] neg_hi:[0,1]
	v_fmac_f32_e32 v78, v2, v2
	v_pk_mul_f32 v[4:5], v[8:9], v[8:9]
	v_pk_add_f32 v[82:83], v[6:7], v[0:1] op_sel_hi:[1,0] neg_lo:[0,1] neg_hi:[0,1]
	v_add_f32_e32 v4, v4, v78
	v_add_f32_e32 v78, v5, v4
	v_pk_mul_f32 v[4:5], v[82:83], v[82:83]
	s_nop 0
	v_add_f32_e32 v0, v4, v78
	v_add_f32_e32 v0, v5, v0
	s_nop 0
	s_waitcnt lgkmcnt(0)
	s_nop 1
	v_add_f32_dpp v0, v0, v0 quad_perm:[1,0,3,2] row_mask:0xf bank_mask:0xf
	s_nop 0
	s_waitcnt lgkmcnt(0)
	s_nop 1
	v_add_f32_dpp v0, v0, v0 quad_perm:[2,3,0,1] row_mask:0xf bank_mask:0xf
	s_nop 0
	s_waitcnt lgkmcnt(0)
	s_nop 1
	v_add_f32_dpp v0, v0, v0 row_half_mirror row_mask:0xf bank_mask:0xf
	s_nop 0
	s_waitcnt lgkmcnt(0)
	s_nop 1
	v_add_f32_dpp v0, v0, v0 row_mirror row_mask:0xf bank_mask:0xf
	v_mov_b32_e32 v4, v0
	s_nop 1
	v_permlane16_swap_b32_e32 v0, v4
	s_waitcnt lgkmcnt(0)
	v_add_f32_e32 v0, v0, v4
	v_mov_b32_e32 v4, v0
	s_nop 1
	v_permlane32_swap_b32_e32 v0, v4
	s_waitcnt lgkmcnt(0)
	v_add_f32_e32 v0, v0, v4
	v_fmamk_f32 v0, v0, 0x3b2aaaab, v162
	v_cmp_gt_f32_e64 s[42:43], s11, v0
	v_mul_f32_e32 v4, 0x4b800000, v0
	s_nop 0
	v_cndmask_b32_e64 v0, v0, v4, s[42:43]
	v_rsq_f32_e32 v0, v0
	s_nop 0
	v_mul_f32_e32 v4, 0x45800000, v0
	v_cndmask_b32_e64 v0, v0, v4, s[42:43]
	v_mul_f32_e32 v2, v2, v0
	v_fma_f32 v2, v14, v2, v20
	v_mul_f32_e32 v4, 0xbfb8aa3b, v2
	v_exp_f32_e32 v4, v4
	s_nop 0
	v_add_f32_e32 v4, 1.0, v4
	v_rcp_f32_e32 v4, v4
	s_nop 0
	v_mul_f32_e32 v4, v2, v4
	v_mul_f32_e32 v2, v3, v0
	v_fma_f32 v2, v15, v2, v21
	v_mul_f32_e32 v3, 0xbfb8aa3b, v2
	v_exp_f32_e32 v3, v3
	s_nop 0
	v_add_f32_e32 v3, 1.0, v3
	v_rcp_f32_e32 v3, v3
	s_nop 0
	v_mul_f32_e32 v5, v2, v3
	v_mul_f32_e32 v2, v8, v0
	v_fma_f32 v2, v16, v2, v22
	v_mul_f32_e32 v3, 0xbfb8aa3b, v2
	v_exp_f32_e32 v3, v3
	v_cvt_pk_bf16_f32 v4, v4, v5
	s_nop 0
	v_add_f32_e32 v3, 1.0, v3
	v_rcp_f32_e32 v3, v3
	s_nop 0
	v_mul_f32_e32 v6, v2, v3
	v_mul_f32_e32 v2, v9, v0
	v_fma_f32 v81, v17, v2, v23
	v_mul_f32_e32 v2, 0xbfb8aa3b, v81
	v_exp_f32_e32 v2, v2
	s_nop 0
	v_add_f32_e32 v2, 1.0, v2
	v_rcp_f32_e32 v2, v2
	s_nop 0
	v_mul_f32_e32 v7, v81, v2
	v_mul_f32_e32 v2, v82, v0
	v_mul_f32_e32 v0, v83, v0
	v_fma_f32 v2, v18, v2, v10
	v_fma_f32 v87, v19, v0, v11
	v_mul_f32_e32 v3, 0xbfb8aa3b, v2
	v_mul_f32_e32 v0, 0xbfb8aa3b, v87
	v_exp_f32_e32 v3, v3
	v_exp_f32_e32 v0, v0
	v_add_f32_e32 v3, 1.0, v3
	v_add_f32_e32 v0, 1.0, v0
	v_rcp_f32_e32 v3, v3
	v_rcp_f32_e32 v0, v0
	v_mul_f32_e32 v8, v2, v3
	v_mul_f32_e32 v0, v87, v0
	v_lshl_add_u64 v[2:3], v[76:77], 0, s[0:1]
	global_store_dword v[2:3], v4, off offset:1280
	v_cvt_pk_bf16_f32 v4, v6, v7
	global_store_dword v[2:3], v4, off offset:1284
	v_cvt_pk_bf16_f32 v0, v8, v0
	s_mul_i32 s0, s91, 0x600
	global_store_dword v[2:3], v0, off offset:1288
	v_add_u32_e32 v0, s0, v12
	ds_read2_b64 v[2:5], v0 offset1:1
	s_add_i32 s0, s13, s91
	s_ashr_i32 s1, s0, 31
	s_lshl_b64 s[0:1], s[0:1], 11
	s_waitcnt lgkmcnt(0)
	v_add_f32_e32 v6, 0, v2
	v_add_f32_e32 v8, v6, v3
	ds_read_b64 v[6:7], v0 offset:16
	v_add_f32_e32 v8, v8, v4
	v_add_f32_e32 v8, v8, v5
	s_waitcnt lgkmcnt(0)
	v_add_f32_e32 v8, v8, v6
	v_add_f32_e32 v8, v8, v7
	s_nop 0
	s_waitcnt lgkmcnt(0)
	s_nop 1
	v_add_f32_dpp v8, v8, v8 quad_perm:[1,0,3,2] row_mask:0xf bank_mask:0xf
	s_nop 0
	s_waitcnt lgkmcnt(0)
	s_nop 1
	v_add_f32_dpp v8, v8, v8 quad_perm:[2,3,0,1] row_mask:0xf bank_mask:0xf
	s_nop 0
	s_waitcnt lgkmcnt(0)
	s_nop 1
	v_add_f32_dpp v8, v8, v8 row_half_mirror row_mask:0xf bank_mask:0xf
	s_nop 0
	s_waitcnt lgkmcnt(0)
	s_nop 1
	v_add_f32_dpp v8, v8, v8 row_mirror row_mask:0xf bank_mask:0xf
	v_mov_b32_e32 v9, v8
	s_nop 1
	v_permlane16_swap_b32_e32 v8, v9
	s_waitcnt lgkmcnt(0)
	v_add_f32_e32 v8, v8, v9
	v_mov_b32_e32 v9, v8
	s_nop 1
	v_permlane32_swap_b32_e32 v8, v9
	s_waitcnt lgkmcnt(0)
	v_add_f32_e32 v9, v8, v9
	v_fmac_f32_e32 v3, 0xbb2aaaab, v9
	v_mul_f32_e32 v8, 0x3b2aaaab, v9
	v_fmamk_f32 v2, v9, 0xbb2aaaab, v2
	v_mul_f32_e32 v9, v3, v3
	v_fmac_f32_e32 v9, v2, v2
	v_pk_add_f32 v[82:83], v[4:5], v[8:9] op_sel_hi:[1,0] neg_lo:[0,1] neg_hi:[0,1]
	s_nop 0
	v_pk_mul_f32 v[4:5], v[82:83], v[82:83]
	s_nop 0
	v_add_f32_e32 v4, v4, v9
	v_pk_add_f32 v[8:9], v[6:7], v[8:9] op_sel_hi:[1,0] neg_lo:[0,1] neg_hi:[0,1]
	v_add_f32_e32 v78, v5, v4
	v_pk_mul_f32 v[4:5], v[8:9], v[8:9]
	s_nop 0
	v_add_f32_e32 v4, v4, v78
	v_add_f32_e32 v4, v5, v4
	s_nop 0
	s_waitcnt lgkmcnt(0)
	s_nop 1
	v_add_f32_dpp v4, v4, v4 quad_perm:[1,0,3,2] row_mask:0xf bank_mask:0xf
	s_nop 0
	s_waitcnt lgkmcnt(0)
	s_nop 1
	v_add_f32_dpp v4, v4, v4 quad_perm:[2,3,0,1] row_mask:0xf bank_mask:0xf
	s_nop 0
	s_waitcnt lgkmcnt(0)
	s_nop 1
	v_add_f32_dpp v4, v4, v4 row_half_mirror row_mask:0xf bank_mask:0xf
	s_nop 0
	s_waitcnt lgkmcnt(0)
	s_nop 1
	v_add_f32_dpp v4, v4, v4 row_mirror row_mask:0xf bank_mask:0xf
	v_mov_b32_e32 v5, v4
	s_nop 1
	v_permlane16_swap_b32_e32 v4, v5
	s_waitcnt lgkmcnt(0)
	v_add_f32_e32 v4, v4, v5
	v_mov_b32_e32 v5, v4
	s_nop 1
	v_permlane32_swap_b32_e32 v4, v5
	s_waitcnt lgkmcnt(0)
	v_add_f32_e32 v4, v4, v5
	v_fmamk_f32 v4, v4, 0x3b2aaaab, v162
	v_cmp_gt_f32_e64 s[42:43], s11, v4
	v_mul_f32_e32 v5, 0x4b800000, v4
	s_nop 0
	v_cndmask_b32_e64 v4, v4, v5, s[42:43]
	v_rsq_f32_e32 v4, v4
	s_nop 0
	v_mul_f32_e32 v5, 0x45800000, v4
	v_cndmask_b32_e64 v88, v4, v5, s[42:43]
	v_mul_f32_e32 v2, v2, v88
	v_mul_f32_e32 v3, v3, v88
	v_fma_f32 v2, v14, v2, v20
	v_mul_f32_e32 v4, 0xbfb8aa3b, v2
	v_exp_f32_e32 v4, v4
	v_fma_f32 v3, v15, v3, v21
	v_add_f32_e32 v4, 1.0, v4
	v_rcp_f32_e32 v4, v4
	s_nop 0
	v_mul_f32_e32 v2, v2, v4
	v_mul_f32_e32 v4, 0xbfb8aa3b, v3
	v_exp_f32_e32 v4, v4
	s_nop 0
	v_add_f32_e32 v4, 1.0, v4
	v_rcp_f32_e32 v4, v4
	s_nop 0
	v_mul_f32_e32 v3, v3, v4
	v_mul_f32_e32 v4, v82, v88
	v_fma_f32 v4, v16, v4, v22
	v_mul_f32_e32 v5, 0xbfb8aa3b, v4
	v_exp_f32_e32 v5, v5
	v_mul_f32_e32 v6, v8, v88
	v_fma_f32 v6, v18, v6, v10
	v_cvt_pk_bf16_f32 v2, v2, v3
	v_add_f32_e32 v5, 1.0, v5
	v_rcp_f32_e32 v5, v5
	s_nop 0
	v_mul_f32_e32 v4, v4, v5
	v_mul_f32_e32 v5, v83, v88
	v_fma_f32 v81, v17, v5, v23
	v_mul_f32_e32 v7, 0xbfb8aa3b, v6
	v_exp_f32_e32 v7, v7
	v_mul_f32_e32 v5, 0xbfb8aa3b, v81
	v_exp_f32_e32 v5, v5
	v_add_f32_e32 v7, 1.0, v7
	v_rcp_f32_e32 v7, v7
	v_add_f32_e32 v5, 1.0, v5
	v_rcp_f32_e32 v5, v5
	v_mul_f32_e32 v6, v6, v7
	v_mul_f32_e32 v7, v9, v88
	v_fma_f32 v87, v19, v7, v11
	v_mul_f32_e32 v7, 0xbfb8aa3b, v87
	v_exp_f32_e32 v7, v7
	v_lshl_add_u64 v[8:9], v[76:77], 0, s[0:1]
	v_mul_f32_e32 v5, v81, v5
	global_store_dword v[8:9], v2, off offset:1280
	v_add_f32_e32 v7, 1.0, v7
	v_rcp_f32_e32 v7, v7
	v_cvt_pk_bf16_f32 v2, v4, v5
	global_store_dword v[8:9], v2, off offset:1284
	s_add_i32 s0, s13, s93
	v_mul_f32_e32 v7, v87, v7
	v_cvt_pk_bf16_f32 v2, v6, v7
	global_store_dword v[8:9], v2, off offset:1288
	ds_read2_b64 v[2:5], v0 offset0:192 offset1:193
	s_ashr_i32 s1, s0, 31
	s_lshl_b64 s[0:1], s[0:1], 11
	s_waitcnt lgkmcnt(0)
	v_add_f32_e32 v6, 0, v2
	v_add_f32_e32 v8, v6, v3
	ds_read_b64 v[6:7], v0 offset:1552
	v_add_f32_e32 v8, v8, v4
	v_add_f32_e32 v8, v8, v5
	s_waitcnt lgkmcnt(0)
	v_add_f32_e32 v8, v8, v6
	v_add_f32_e32 v8, v8, v7
	s_nop 0
	s_waitcnt lgkmcnt(0)
	s_nop 1
	v_add_f32_dpp v8, v8, v8 quad_perm:[1,0,3,2] row_mask:0xf bank_mask:0xf
	s_nop 0
	s_waitcnt lgkmcnt(0)
	s_nop 1
	v_add_f32_dpp v8, v8, v8 quad_perm:[2,3,0,1] row_mask:0xf bank_mask:0xf
	s_nop 0
	s_waitcnt lgkmcnt(0)
	s_nop 1
	v_add_f32_dpp v8, v8, v8 row_half_mirror row_mask:0xf bank_mask:0xf
	s_nop 0
	s_waitcnt lgkmcnt(0)
	s_nop 1
	v_add_f32_dpp v8, v8, v8 row_mirror row_mask:0xf bank_mask:0xf
	v_mov_b32_e32 v9, v8
	s_nop 1
	v_permlane16_swap_b32_e32 v8, v9
	s_waitcnt lgkmcnt(0)
	v_add_f32_e32 v8, v8, v9
	v_mov_b32_e32 v9, v8
	s_nop 1
	v_permlane32_swap_b32_e32 v8, v9
	s_waitcnt lgkmcnt(0)
	v_add_f32_e32 v9, v8, v9
	v_fmac_f32_e32 v3, 0xbb2aaaab, v9
	v_mul_f32_e32 v8, 0x3b2aaaab, v9
	v_fmamk_f32 v2, v9, 0xbb2aaaab, v2
	v_mul_f32_e32 v9, v3, v3
	v_fmac_f32_e32 v9, v2, v2
	v_pk_add_f32 v[82:83], v[4:5], v[8:9] op_sel_hi:[1,0] neg_lo:[0,1] neg_hi:[0,1]
	s_nop 0
	v_pk_mul_f32 v[4:5], v[82:83], v[82:83]
	s_nop 0
	v_add_f32_e32 v4, v4, v9
	v_pk_add_f32 v[8:9], v[6:7], v[8:9] op_sel_hi:[1,0] neg_lo:[0,1] neg_hi:[0,1]
	v_add_f32_e32 v78, v5, v4
	v_pk_mul_f32 v[4:5], v[8:9], v[8:9]
	s_nop 0
	v_add_f32_e32 v4, v4, v78
	v_add_f32_e32 v4, v5, v4
	s_nop 0
	s_waitcnt lgkmcnt(0)
	s_nop 1
	v_add_f32_dpp v4, v4, v4 quad_perm:[1,0,3,2] row_mask:0xf bank_mask:0xf
	s_nop 0
	s_waitcnt lgkmcnt(0)
	s_nop 1
	v_add_f32_dpp v4, v4, v4 quad_perm:[2,3,0,1] row_mask:0xf bank_mask:0xf
	s_nop 0
	s_waitcnt lgkmcnt(0)
	s_nop 1
	v_add_f32_dpp v4, v4, v4 row_half_mirror row_mask:0xf bank_mask:0xf
	s_nop 0
	s_waitcnt lgkmcnt(0)
	s_nop 1
	v_add_f32_dpp v4, v4, v4 row_mirror row_mask:0xf bank_mask:0xf
	v_mov_b32_e32 v5, v4
	s_nop 1
	v_permlane16_swap_b32_e32 v4, v5
	s_waitcnt lgkmcnt(0)
	v_add_f32_e32 v4, v4, v5
	v_mov_b32_e32 v5, v4
	s_nop 1
	v_permlane32_swap_b32_e32 v4, v5
	s_waitcnt lgkmcnt(0)
	v_add_f32_e32 v4, v4, v5
	v_fmamk_f32 v4, v4, 0x3b2aaaab, v162
	v_cmp_gt_f32_e64 s[42:43], s11, v4
	v_mul_f32_e32 v5, 0x4b800000, v4
	s_nop 0
	v_cndmask_b32_e64 v4, v4, v5, s[42:43]
	v_rsq_f32_e32 v4, v4
	s_nop 0
	v_mul_f32_e32 v5, 0x45800000, v4
	v_cndmask_b32_e64 v88, v4, v5, s[42:43]
	v_mul_f32_e32 v2, v2, v88
	v_fma_f32 v2, v14, v2, v20
	v_mul_f32_e32 v4, 0xbfb8aa3b, v2
	v_exp_f32_e32 v4, v4
	s_nop 0
	v_add_f32_e32 v4, 1.0, v4
	v_rcp_f32_e32 v4, v4
	s_nop 0
	v_mul_f32_e32 v4, v2, v4
	v_mul_f32_e32 v2, v3, v88
	v_fma_f32 v2, v15, v2, v21
	v_mul_f32_e32 v3, 0xbfb8aa3b, v2
	v_exp_f32_e32 v3, v3
	s_nop 0
	v_add_f32_e32 v3, 1.0, v3
	v_rcp_f32_e32 v3, v3
	s_nop 0
	v_mul_f32_e32 v5, v2, v3
	v_mul_f32_e32 v2, v82, v88
	v_fma_f32 v2, v16, v2, v22
	v_mul_f32_e32 v3, 0xbfb8aa3b, v2
	v_exp_f32_e32 v3, v3
	v_cvt_pk_bf16_f32 v4, v4, v5
	s_nop 0
	v_add_f32_e32 v3, 1.0, v3
	v_rcp_f32_e32 v3, v3
	s_nop 0
	v_mul_f32_e32 v6, v2, v3
	v_mul_f32_e32 v2, v83, v88
	v_fma_f32 v81, v17, v2, v23
	v_mul_f32_e32 v2, 0xbfb8aa3b, v81
	v_exp_f32_e32 v2, v2
	s_nop 0
	v_add_f32_e32 v2, 1.0, v2
	v_rcp_f32_e32 v2, v2
	s_nop 0
	v_mul_f32_e32 v7, v81, v2
	v_mul_f32_e32 v2, v8, v88
	v_fma_f32 v2, v18, v2, v10
	v_mul_f32_e32 v3, 0xbfb8aa3b, v2
	v_exp_f32_e32 v3, v3
	s_nop 0
	v_add_f32_e32 v3, 1.0, v3
	v_rcp_f32_e32 v3, v3
	s_nop 0
	v_mul_f32_e32 v8, v2, v3
	v_mul_f32_e32 v2, v9, v88
	v_fma_f32 v87, v19, v2, v11
	v_mul_f32_e32 v2, 0xbfb8aa3b, v87
	v_exp_f32_e32 v2, v2
	s_nop 0
	v_add_f32_e32 v2, 1.0, v2
	v_rcp_f32_e32 v2, v2
	s_nop 0
	v_mul_f32_e32 v9, v87, v2
	v_lshl_add_u64 v[2:3], v[76:77], 0, s[0:1]
	global_store_dword v[2:3], v4, off offset:1280
	v_cvt_pk_bf16_f32 v4, v6, v7
	global_store_dword v[2:3], v4, off offset:1284
	v_cvt_pk_bf16_f32 v4, v8, v9
	global_store_dword v[2:3], v4, off offset:1288
	v_add_u32_e32 v2, 0xc00, v0
	ds_read2_b64 v[2:5], v2 offset1:1
	s_add_i32 s0, s13, s28
	s_ashr_i32 s1, s0, 31
	s_lshl_b64 s[0:1], s[0:1], 11
	s_cmpk_lt_i32 s12, 0x400
	s_waitcnt lgkmcnt(0)
	v_add_f32_e32 v6, 0, v2
	v_add_f32_e32 v8, v6, v3
	ds_read_b64 v[6:7], v0 offset:3088
	v_add_f32_e32 v0, v8, v4
	v_add_f32_e32 v0, v0, v5
	s_waitcnt lgkmcnt(0)
	v_add_f32_e32 v0, v0, v6
	v_add_f32_e32 v0, v0, v7
	s_nop 0
	s_waitcnt lgkmcnt(0)
	s_nop 1
	v_add_f32_dpp v0, v0, v0 quad_perm:[1,0,3,2] row_mask:0xf bank_mask:0xf
	s_nop 0
	s_waitcnt lgkmcnt(0)
	s_nop 1
	v_add_f32_dpp v0, v0, v0 quad_perm:[2,3,0,1] row_mask:0xf bank_mask:0xf
	s_nop 0
	s_waitcnt lgkmcnt(0)
	s_nop 1
	v_add_f32_dpp v0, v0, v0 row_half_mirror row_mask:0xf bank_mask:0xf
	s_nop 0
	s_waitcnt lgkmcnt(0)
	s_nop 1
	v_add_f32_dpp v0, v0, v0 row_mirror row_mask:0xf bank_mask:0xf
	v_mov_b32_e32 v8, v0
	s_nop 1
	v_permlane16_swap_b32_e32 v0, v8
	s_waitcnt lgkmcnt(0)
	v_add_f32_e32 v0, v0, v8
	v_mov_b32_e32 v8, v0
	s_nop 1
	v_permlane32_swap_b32_e32 v0, v8
	s_waitcnt lgkmcnt(0)
	v_add_f32_e32 v8, v0, v8
	v_mul_f32_e32 v0, 0x3b2aaaab, v8
	v_fmac_f32_e32 v3, 0xbb2aaaab, v8
	v_fmamk_f32 v2, v8, 0xbb2aaaab, v2
	v_mul_f32_e32 v78, v3, v3
	v_pk_add_f32 v[8:9], v[4:5], v[0:1] op_sel_hi:[1,0] neg_lo:[0,1] neg_hi:[0,1]
	v_fmac_f32_e32 v78, v2, v2
	v_pk_mul_f32 v[4:5], v[8:9], v[8:9]
	v_pk_add_f32 v[82:83], v[6:7], v[0:1] op_sel_hi:[1,0] neg_lo:[0,1] neg_hi:[0,1]
	v_add_f32_e32 v4, v4, v78
	v_add_f32_e32 v78, v5, v4
	v_pk_mul_f32 v[4:5], v[82:83], v[82:83]
	s_nop 0
	v_add_f32_e32 v0, v4, v78
	v_add_f32_e32 v0, v5, v0
	s_nop 0
	s_waitcnt lgkmcnt(0)
	s_nop 1
	v_add_f32_dpp v0, v0, v0 quad_perm:[1,0,3,2] row_mask:0xf bank_mask:0xf
	s_nop 0
	s_waitcnt lgkmcnt(0)
	s_nop 1
	v_add_f32_dpp v0, v0, v0 quad_perm:[2,3,0,1] row_mask:0xf bank_mask:0xf
	s_nop 0
	s_waitcnt lgkmcnt(0)
	s_nop 1
	v_add_f32_dpp v0, v0, v0 row_half_mirror row_mask:0xf bank_mask:0xf
	s_nop 0
	s_waitcnt lgkmcnt(0)
	s_nop 1
	v_add_f32_dpp v0, v0, v0 row_mirror row_mask:0xf bank_mask:0xf
	v_mov_b32_e32 v4, v0
	s_nop 1
	v_permlane16_swap_b32_e32 v0, v4
	s_waitcnt lgkmcnt(0)
	v_add_f32_e32 v0, v0, v4
	v_mov_b32_e32 v4, v0
	s_nop 1
	v_permlane32_swap_b32_e32 v0, v4
	s_waitcnt lgkmcnt(0)
	v_add_f32_e32 v0, v0, v4
	v_fmamk_f32 v0, v0, 0x3b2aaaab, v162
	v_cmp_gt_f32_e64 s[42:43], s11, v0
	v_mul_f32_e32 v4, 0x4b800000, v0
	s_nop 0
	v_cndmask_b32_e64 v0, v0, v4, s[42:43]
	v_rsq_f32_e32 v0, v0
	s_nop 0
	v_mul_f32_e32 v4, 0x45800000, v0
	v_cndmask_b32_e64 v0, v0, v4, s[42:43]
	v_mul_f32_e32 v2, v2, v0
	v_fma_f32 v2, v14, v2, v20
	v_mul_f32_e32 v4, 0xbfb8aa3b, v2
	v_exp_f32_e32 v4, v4
	s_nop 0
	v_add_f32_e32 v4, 1.0, v4
	v_rcp_f32_e32 v4, v4
	s_nop 0
	v_mul_f32_e32 v4, v2, v4
	v_mul_f32_e32 v2, v3, v0
	v_fma_f32 v2, v15, v2, v21
	v_mul_f32_e32 v3, 0xbfb8aa3b, v2
	v_exp_f32_e32 v3, v3
	s_nop 0
	v_add_f32_e32 v3, 1.0, v3
	v_rcp_f32_e32 v3, v3
	s_nop 0
	v_mul_f32_e32 v5, v2, v3
	v_mul_f32_e32 v2, v8, v0
	v_fma_f32 v2, v16, v2, v22
	v_mul_f32_e32 v3, 0xbfb8aa3b, v2
	v_exp_f32_e32 v3, v3
	v_cvt_pk_bf16_f32 v4, v4, v5
	s_nop 0
	v_add_f32_e32 v3, 1.0, v3
	v_rcp_f32_e32 v3, v3
	s_nop 0
	v_mul_f32_e32 v6, v2, v3
	v_mul_f32_e32 v2, v9, v0
	v_fma_f32 v81, v17, v2, v23
	v_mul_f32_e32 v2, 0xbfb8aa3b, v81
	v_exp_f32_e32 v2, v2
	s_nop 0
	v_add_f32_e32 v2, 1.0, v2
	v_rcp_f32_e32 v2, v2
	s_nop 0
	v_mul_f32_e32 v7, v81, v2
	v_mul_f32_e32 v2, v82, v0
	v_mul_f32_e32 v0, v83, v0
	v_fma_f32 v2, v18, v2, v10
	v_fma_f32 v87, v19, v0, v11
	v_mul_f32_e32 v3, 0xbfb8aa3b, v2
	v_mul_f32_e32 v0, 0xbfb8aa3b, v87
	v_exp_f32_e32 v3, v3
	v_exp_f32_e32 v0, v0
	v_add_f32_e32 v3, 1.0, v3
	v_add_f32_e32 v0, 1.0, v0
	v_rcp_f32_e32 v3, v3
	v_rcp_f32_e32 v0, v0
	v_mul_f32_e32 v8, v2, v3
	v_mul_f32_e32 v0, v87, v0
	v_lshl_add_u64 v[2:3], v[76:77], 0, s[0:1]
	global_store_dword v[2:3], v4, off offset:1280
	v_cvt_pk_bf16_f32 v4, v6, v7
	global_store_dword v[2:3], v4, off offset:1284
	v_cvt_pk_bf16_f32 v0, v8, v0
	global_store_dword v[2:3], v0, off offset:1288
	s_cbranch_scc0 .LBB7_813
	.p2align	6
.LBB7_806:
	s_lshl_b32 s13, s12, 5
	s_waitcnt vmcnt(0)
	s_barrier
	s_and_saveexec_b64 s[0:1], vcc
	s_cbranch_execz .LBB7_811
	s_and_b32 s3, s13, 0x7e0
	s_sub_i32 s3, 29, s3
	v_lshl_add_u32 v78, v150, 5, 0
	s_mov_b32 s5, 0x2aaaaaab
	v_mov_b32_e32 v79, v150
	v_mul_hi_i32 v80, v79, s5
	v_lshrrev_b32_e32 v81, 31, v80
	v_ashrrev_i32_e32 v80, 3, v80
	v_add_u32_e32 v80, v80, v81
	v_cmp_lt_i32_e64 s[42:43], s3, v80
	s_nop 1
	v_mov_b64_e32 v[2:3], 0
	v_mov_b64_e32 v[4:5], 0
	v_mov_b64_e32 v[6:7], 0
	v_mov_b64_e32 v[8:9], 0
	s_and_saveexec_b64 s[8:9], s[42:43]
	v_lshlrev_b32_e32 v2, 16, v28
	v_and_b32_e32 v3, 0xffff0000, v28
	v_lshlrev_b32_e32 v4, 16, v29
	v_and_b32_e32 v5, 0xffff0000, v29
	v_lshlrev_b32_e32 v6, 16, v30
	v_and_b32_e32 v7, 0xffff0000, v30
	v_lshlrev_b32_e32 v8, 16, v31
	v_and_b32_e32 v9, 0xffff0000, v31
	v_mul_f32_e32 v2, 0xbfb8aa3b, v2
	v_mul_f32_e32 v3, 0xbfb8aa3b, v3
	v_mul_f32_e32 v4, 0xbfb8aa3b, v4
	v_mul_f32_e32 v5, 0xbfb8aa3b, v5
	v_mul_f32_e32 v6, 0xbfb8aa3b, v6
	v_mul_f32_e32 v7, 0xbfb8aa3b, v7
	v_mul_f32_e32 v8, 0xbfb8aa3b, v8
	v_mul_f32_e32 v9, 0xbfb8aa3b, v9
	v_exp_f32_e32 v2, v2
	v_exp_f32_e32 v3, v3
	v_exp_f32_e32 v4, v4
	v_exp_f32_e32 v5, v5
	v_exp_f32_e32 v6, v6
	v_exp_f32_e32 v7, v7
	v_exp_f32_e32 v8, v8
	v_exp_f32_e32 v9, v9
	v_add_f32_e32 v2, 1.0, v2
	v_add_f32_e32 v3, 1.0, v3
	v_add_f32_e32 v4, 1.0, v4
	v_add_f32_e32 v5, 1.0, v5
	v_add_f32_e32 v6, 1.0, v6
	v_add_f32_e32 v7, 1.0, v7
	v_add_f32_e32 v8, 1.0, v8
	v_add_f32_e32 v9, 1.0, v9
	v_rcp_f32_e32 v2, v2
	v_rcp_f32_e32 v3, v3
	v_rcp_f32_e32 v4, v4
	v_rcp_f32_e32 v5, v5
	v_rcp_f32_e32 v6, v6
	v_rcp_f32_e32 v7, v7
	v_rcp_f32_e32 v8, v8
	v_rcp_f32_e32 v9, v9
	v_lshlrev_b32_e32 v80, 16, v24
	v_and_b32_e32 v81, 0xffff0000, v24
	v_lshlrev_b32_e32 v82, 16, v25
	v_and_b32_e32 v83, 0xffff0000, v25
	v_lshlrev_b32_e32 v84, 16, v26
	v_and_b32_e32 v85, 0xffff0000, v26
	v_lshlrev_b32_e32 v86, 16, v27
	v_and_b32_e32 v87, 0xffff0000, v27
	v_mul_f32_e32 v2, v2, v80
	v_mul_f32_e32 v3, v3, v81
	v_mul_f32_e32 v4, v4, v82
	v_mul_f32_e32 v5, v5, v83
	v_mul_f32_e32 v6, v6, v84
	v_mul_f32_e32 v7, v7, v85
	v_mul_f32_e32 v8, v8, v86
	v_mul_f32_e32 v9, v9, v87
	s_or_b64 exec, exec, s[8:9]
	ds_write_b128 v78, v[2:5]
	ds_write_b128 v78, v[6:9] offset:16
	v_add_u32_e32 v79, 512, v150
	v_mul_hi_i32 v80, v79, s5
	v_lshrrev_b32_e32 v81, 31, v80
	v_ashrrev_i32_e32 v80, 3, v80
	v_add_u32_e32 v80, v80, v81
	v_cmp_lt_i32_e64 s[42:43], s3, v80
	s_nop 1
	v_mov_b64_e32 v[2:3], 0
	v_mov_b64_e32 v[4:5], 0
	v_mov_b64_e32 v[6:7], 0
	v_mov_b64_e32 v[8:9], 0
	s_and_saveexec_b64 s[8:9], s[42:43]
	v_lshlrev_b32_e32 v2, 16, v36
	v_and_b32_e32 v3, 0xffff0000, v36
	v_lshlrev_b32_e32 v4, 16, v37
	v_and_b32_e32 v5, 0xffff0000, v37
	v_lshlrev_b32_e32 v6, 16, v38
	v_and_b32_e32 v7, 0xffff0000, v38
	v_lshlrev_b32_e32 v8, 16, v39
	v_and_b32_e32 v9, 0xffff0000, v39
	v_mul_f32_e32 v2, 0xbfb8aa3b, v2
	v_mul_f32_e32 v3, 0xbfb8aa3b, v3
	v_mul_f32_e32 v4, 0xbfb8aa3b, v4
	v_mul_f32_e32 v5, 0xbfb8aa3b, v5
	v_mul_f32_e32 v6, 0xbfb8aa3b, v6
	v_mul_f32_e32 v7, 0xbfb8aa3b, v7
	v_mul_f32_e32 v8, 0xbfb8aa3b, v8
	v_mul_f32_e32 v9, 0xbfb8aa3b, v9
	v_exp_f32_e32 v2, v2
	v_exp_f32_e32 v3, v3
	v_exp_f32_e32 v4, v4
	v_exp_f32_e32 v5, v5
	v_exp_f32_e32 v6, v6
	v_exp_f32_e32 v7, v7
	v_exp_f32_e32 v8, v8
	v_exp_f32_e32 v9, v9
	v_add_f32_e32 v2, 1.0, v2
	v_add_f32_e32 v3, 1.0, v3
	v_add_f32_e32 v4, 1.0, v4
	v_add_f32_e32 v5, 1.0, v5
	v_add_f32_e32 v6, 1.0, v6
	v_add_f32_e32 v7, 1.0, v7
	v_add_f32_e32 v8, 1.0, v8
	v_add_f32_e32 v9, 1.0, v9
	v_rcp_f32_e32 v2, v2
	v_rcp_f32_e32 v3, v3
	v_rcp_f32_e32 v4, v4
	v_rcp_f32_e32 v5, v5
	v_rcp_f32_e32 v6, v6
	v_rcp_f32_e32 v7, v7
	v_rcp_f32_e32 v8, v8
	v_rcp_f32_e32 v9, v9
	v_lshlrev_b32_e32 v80, 16, v32
	v_and_b32_e32 v81, 0xffff0000, v32
	v_lshlrev_b32_e32 v82, 16, v33
	v_and_b32_e32 v83, 0xffff0000, v33
	v_lshlrev_b32_e32 v84, 16, v34
	v_and_b32_e32 v85, 0xffff0000, v34
	v_lshlrev_b32_e32 v86, 16, v35
	v_and_b32_e32 v87, 0xffff0000, v35
	v_mul_f32_e32 v2, v2, v80
	v_mul_f32_e32 v3, v3, v81
	v_mul_f32_e32 v4, v4, v82
	v_mul_f32_e32 v5, v5, v83
	v_mul_f32_e32 v6, v6, v84
	v_mul_f32_e32 v7, v7, v85
	v_mul_f32_e32 v8, v8, v86
	v_mul_f32_e32 v9, v9, v87
	s_or_b64 exec, exec, s[8:9]
	ds_write_b128 v78, v[2:5] offset:16384
	ds_write_b128 v78, v[6:9] offset:16400
	v_add_u32_e32 v79, 1024, v150
	v_mul_hi_i32 v80, v79, s5
	v_lshrrev_b32_e32 v81, 31, v80
	v_ashrrev_i32_e32 v80, 3, v80
	v_add_u32_e32 v80, v80, v81
	v_cmp_lt_i32_e64 s[42:43], s3, v80
	s_nop 1
	v_mov_b64_e32 v[2:3], 0
	v_mov_b64_e32 v[4:5], 0
	v_mov_b64_e32 v[6:7], 0
	v_mov_b64_e32 v[8:9], 0
	s_and_saveexec_b64 s[8:9], s[42:43]
	v_lshlrev_b32_e32 v2, 16, v44
	v_and_b32_e32 v3, 0xffff0000, v44
	v_lshlrev_b32_e32 v4, 16, v45
	v_and_b32_e32 v5, 0xffff0000, v45
	v_lshlrev_b32_e32 v6, 16, v46
	v_and_b32_e32 v7, 0xffff0000, v46
	v_lshlrev_b32_e32 v8, 16, v47
	v_and_b32_e32 v9, 0xffff0000, v47
	v_mul_f32_e32 v2, 0xbfb8aa3b, v2
	v_mul_f32_e32 v3, 0xbfb8aa3b, v3
	v_mul_f32_e32 v4, 0xbfb8aa3b, v4
	v_mul_f32_e32 v5, 0xbfb8aa3b, v5
	v_mul_f32_e32 v6, 0xbfb8aa3b, v6
	v_mul_f32_e32 v7, 0xbfb8aa3b, v7
	v_mul_f32_e32 v8, 0xbfb8aa3b, v8
	v_mul_f32_e32 v9, 0xbfb8aa3b, v9
	v_exp_f32_e32 v2, v2
	v_exp_f32_e32 v3, v3
	v_exp_f32_e32 v4, v4
	v_exp_f32_e32 v5, v5
	v_exp_f32_e32 v6, v6
	v_exp_f32_e32 v7, v7
	v_exp_f32_e32 v8, v8
	v_exp_f32_e32 v9, v9
	v_add_f32_e32 v2, 1.0, v2
	v_add_f32_e32 v3, 1.0, v3
	v_add_f32_e32 v4, 1.0, v4
	v_add_f32_e32 v5, 1.0, v5
	v_add_f32_e32 v6, 1.0, v6
	v_add_f32_e32 v7, 1.0, v7
	v_add_f32_e32 v8, 1.0, v8
	v_add_f32_e32 v9, 1.0, v9
	v_rcp_f32_e32 v2, v2
	v_rcp_f32_e32 v3, v3
	v_rcp_f32_e32 v4, v4
	v_rcp_f32_e32 v5, v5
	v_rcp_f32_e32 v6, v6
	v_rcp_f32_e32 v7, v7
	v_rcp_f32_e32 v8, v8
	v_rcp_f32_e32 v9, v9
	v_lshlrev_b32_e32 v80, 16, v40
	v_and_b32_e32 v81, 0xffff0000, v40
	v_lshlrev_b32_e32 v82, 16, v41
	v_and_b32_e32 v83, 0xffff0000, v41
	v_lshlrev_b32_e32 v84, 16, v42
	v_and_b32_e32 v85, 0xffff0000, v42
	v_lshlrev_b32_e32 v86, 16, v43
	v_and_b32_e32 v87, 0xffff0000, v43
	v_mul_f32_e32 v2, v2, v80
	v_mul_f32_e32 v3, v3, v81
	v_mul_f32_e32 v4, v4, v82
	v_mul_f32_e32 v5, v5, v83
	v_mul_f32_e32 v6, v6, v84
	v_mul_f32_e32 v7, v7, v85
	v_mul_f32_e32 v8, v8, v86
	v_mul_f32_e32 v9, v9, v87
	s_or_b64 exec, exec, s[8:9]
	ds_write_b128 v78, v[2:5] offset:32768
	ds_write_b128 v78, v[6:9] offset:32784
	v_add_u32_e32 v79, 1536, v150
	v_mul_hi_i32 v80, v79, s5
	v_lshrrev_b32_e32 v81, 31, v80
	v_ashrrev_i32_e32 v80, 3, v80
	v_add_u32_e32 v80, v80, v81
	v_cmp_lt_i32_e64 s[42:43], s3, v80
	s_nop 1
	v_mov_b64_e32 v[2:3], 0
	v_mov_b64_e32 v[4:5], 0
	v_mov_b64_e32 v[6:7], 0
	v_mov_b64_e32 v[8:9], 0
	s_and_saveexec_b64 s[8:9], s[42:43]
	v_lshlrev_b32_e32 v2, 16, v52
	v_and_b32_e32 v3, 0xffff0000, v52
	v_lshlrev_b32_e32 v4, 16, v53
	v_and_b32_e32 v5, 0xffff0000, v53
	v_lshlrev_b32_e32 v6, 16, v54
	v_and_b32_e32 v7, 0xffff0000, v54
	v_lshlrev_b32_e32 v8, 16, v55
	v_and_b32_e32 v9, 0xffff0000, v55
	v_mul_f32_e32 v2, 0xbfb8aa3b, v2
	v_mul_f32_e32 v3, 0xbfb8aa3b, v3
	v_mul_f32_e32 v4, 0xbfb8aa3b, v4
	v_mul_f32_e32 v5, 0xbfb8aa3b, v5
	v_mul_f32_e32 v6, 0xbfb8aa3b, v6
	v_mul_f32_e32 v7, 0xbfb8aa3b, v7
	v_mul_f32_e32 v8, 0xbfb8aa3b, v8
	v_mul_f32_e32 v9, 0xbfb8aa3b, v9
	v_exp_f32_e32 v2, v2
	v_exp_f32_e32 v3, v3
	v_exp_f32_e32 v4, v4
	v_exp_f32_e32 v5, v5
	v_exp_f32_e32 v6, v6
	v_exp_f32_e32 v7, v7
	v_exp_f32_e32 v8, v8
	v_exp_f32_e32 v9, v9
	v_add_f32_e32 v2, 1.0, v2
	v_add_f32_e32 v3, 1.0, v3
	v_add_f32_e32 v4, 1.0, v4
	v_add_f32_e32 v5, 1.0, v5
	v_add_f32_e32 v6, 1.0, v6
	v_add_f32_e32 v7, 1.0, v7
	v_add_f32_e32 v8, 1.0, v8
	v_add_f32_e32 v9, 1.0, v9
	v_rcp_f32_e32 v2, v2
	v_rcp_f32_e32 v3, v3
	v_rcp_f32_e32 v4, v4
	v_rcp_f32_e32 v5, v5
	v_rcp_f32_e32 v6, v6
	v_rcp_f32_e32 v7, v7
	v_rcp_f32_e32 v8, v8
	v_rcp_f32_e32 v9, v9
	v_lshlrev_b32_e32 v80, 16, v48
	v_and_b32_e32 v81, 0xffff0000, v48
	v_lshlrev_b32_e32 v82, 16, v49
	v_and_b32_e32 v83, 0xffff0000, v49
	v_lshlrev_b32_e32 v84, 16, v50
	v_and_b32_e32 v85, 0xffff0000, v50
	v_lshlrev_b32_e32 v86, 16, v51
	v_and_b32_e32 v87, 0xffff0000, v51
	v_mul_f32_e32 v2, v2, v80
	v_mul_f32_e32 v3, v3, v81
	v_mul_f32_e32 v4, v4, v82
	v_mul_f32_e32 v5, v5, v83
	v_mul_f32_e32 v6, v6, v84
	v_mul_f32_e32 v7, v7, v85
	v_mul_f32_e32 v8, v8, v86
	v_mul_f32_e32 v9, v9, v87
	s_or_b64 exec, exec, s[8:9]
	ds_write_b128 v78, v[2:5] offset:49152
	ds_write_b128 v78, v[6:9] offset:49168
	v_add_u32_e32 v79, 2048, v150
	v_mul_hi_i32 v80, v79, s5
	v_lshrrev_b32_e32 v81, 31, v80
	v_ashrrev_i32_e32 v80, 3, v80
	v_add_u32_e32 v80, v80, v81
	v_cmp_lt_i32_e64 s[42:43], s3, v80
	s_nop 1
	v_mov_b64_e32 v[2:3], 0
	v_mov_b64_e32 v[4:5], 0
	v_mov_b64_e32 v[6:7], 0
	v_mov_b64_e32 v[8:9], 0
	s_and_saveexec_b64 s[8:9], s[42:43]
	v_lshlrev_b32_e32 v2, 16, v60
	v_and_b32_e32 v3, 0xffff0000, v60
	v_lshlrev_b32_e32 v4, 16, v61
	v_and_b32_e32 v5, 0xffff0000, v61
	v_lshlrev_b32_e32 v6, 16, v62
	v_and_b32_e32 v7, 0xffff0000, v62
	v_lshlrev_b32_e32 v8, 16, v63
	v_and_b32_e32 v9, 0xffff0000, v63
	v_mul_f32_e32 v2, 0xbfb8aa3b, v2
	v_mul_f32_e32 v3, 0xbfb8aa3b, v3
	v_mul_f32_e32 v4, 0xbfb8aa3b, v4
	v_mul_f32_e32 v5, 0xbfb8aa3b, v5
	v_mul_f32_e32 v6, 0xbfb8aa3b, v6
	v_mul_f32_e32 v7, 0xbfb8aa3b, v7
	v_mul_f32_e32 v8, 0xbfb8aa3b, v8
	v_mul_f32_e32 v9, 0xbfb8aa3b, v9
	v_exp_f32_e32 v2, v2
	v_exp_f32_e32 v3, v3
	v_exp_f32_e32 v4, v4
	v_exp_f32_e32 v5, v5
	v_exp_f32_e32 v6, v6
	v_exp_f32_e32 v7, v7
	v_exp_f32_e32 v8, v8
	v_exp_f32_e32 v9, v9
	v_add_f32_e32 v2, 1.0, v2
	v_add_f32_e32 v3, 1.0, v3
	v_add_f32_e32 v4, 1.0, v4
	v_add_f32_e32 v5, 1.0, v5
	v_add_f32_e32 v6, 1.0, v6
	v_add_f32_e32 v7, 1.0, v7
	v_add_f32_e32 v8, 1.0, v8
	v_add_f32_e32 v9, 1.0, v9
	v_rcp_f32_e32 v2, v2
	v_rcp_f32_e32 v3, v3
	v_rcp_f32_e32 v4, v4
	v_rcp_f32_e32 v5, v5
	v_rcp_f32_e32 v6, v6
	v_rcp_f32_e32 v7, v7
	v_rcp_f32_e32 v8, v8
	v_rcp_f32_e32 v9, v9
	v_lshlrev_b32_e32 v80, 16, v56
	v_and_b32_e32 v81, 0xffff0000, v56
	v_lshlrev_b32_e32 v82, 16, v57
	v_and_b32_e32 v83, 0xffff0000, v57
	v_lshlrev_b32_e32 v84, 16, v58
	v_and_b32_e32 v85, 0xffff0000, v58
	v_lshlrev_b32_e32 v86, 16, v59
	v_and_b32_e32 v87, 0xffff0000, v59
	v_mul_f32_e32 v2, v2, v80
	v_mul_f32_e32 v3, v3, v81
	v_mul_f32_e32 v4, v4, v82
	v_mul_f32_e32 v5, v5, v83
	v_mul_f32_e32 v6, v6, v84
	v_mul_f32_e32 v7, v7, v85
	v_mul_f32_e32 v8, v8, v86
	v_mul_f32_e32 v9, v9, v87
	s_or_b64 exec, exec, s[8:9]
	v_add_u32_e32 v79, 0x10000, v78
	ds_write_b128 v79, v[2:5]
	ds_write_b128 v79, v[6:9] offset:16
	v_add_u32_e32 v79, 2560, v150
	v_mul_hi_i32 v80, v79, s5
	v_lshrrev_b32_e32 v81, 31, v80
	v_ashrrev_i32_e32 v80, 3, v80
	v_add_u32_e32 v80, v80, v81
	v_cmp_lt_i32_e64 s[42:43], s3, v80
	s_nop 1
	s_and_b64 s[42:43], s[42:43], s[6:7]
	v_mov_b64_e32 v[2:3], 0
	v_mov_b64_e32 v[4:5], 0
	v_mov_b64_e32 v[6:7], 0
	v_mov_b64_e32 v[8:9], 0
	s_and_saveexec_b64 s[8:9], s[42:43]
	v_lshlrev_b32_e32 v2, 16, v68
	v_and_b32_e32 v3, 0xffff0000, v68
	v_lshlrev_b32_e32 v4, 16, v69
	v_and_b32_e32 v5, 0xffff0000, v69
	v_lshlrev_b32_e32 v6, 16, v70
	v_and_b32_e32 v7, 0xffff0000, v70
	v_lshlrev_b32_e32 v8, 16, v71
	v_and_b32_e32 v9, 0xffff0000, v71
	v_mul_f32_e32 v2, 0xbfb8aa3b, v2
	v_mul_f32_e32 v3, 0xbfb8aa3b, v3
	v_mul_f32_e32 v4, 0xbfb8aa3b, v4
	v_mul_f32_e32 v5, 0xbfb8aa3b, v5
	v_mul_f32_e32 v6, 0xbfb8aa3b, v6
	v_mul_f32_e32 v7, 0xbfb8aa3b, v7
	v_mul_f32_e32 v8, 0xbfb8aa3b, v8
	v_mul_f32_e32 v9, 0xbfb8aa3b, v9
	v_exp_f32_e32 v2, v2
	v_exp_f32_e32 v3, v3
	v_exp_f32_e32 v4, v4
	v_exp_f32_e32 v5, v5
	v_exp_f32_e32 v6, v6
	v_exp_f32_e32 v7, v7
	v_exp_f32_e32 v8, v8
	v_exp_f32_e32 v9, v9
	v_add_f32_e32 v2, 1.0, v2
	v_add_f32_e32 v3, 1.0, v3
	v_add_f32_e32 v4, 1.0, v4
	v_add_f32_e32 v5, 1.0, v5
	v_add_f32_e32 v6, 1.0, v6
	v_add_f32_e32 v7, 1.0, v7
	v_add_f32_e32 v8, 1.0, v8
	v_add_f32_e32 v9, 1.0, v9
	v_rcp_f32_e32 v2, v2
	v_rcp_f32_e32 v3, v3
	v_rcp_f32_e32 v4, v4
	v_rcp_f32_e32 v5, v5
	v_rcp_f32_e32 v6, v6
	v_rcp_f32_e32 v7, v7
	v_rcp_f32_e32 v8, v8
	v_rcp_f32_e32 v9, v9
	v_lshlrev_b32_e32 v80, 16, v64
	v_and_b32_e32 v81, 0xffff0000, v64
	v_lshlrev_b32_e32 v82, 16, v65
	v_and_b32_e32 v83, 0xffff0000, v65
	v_lshlrev_b32_e32 v84, 16, v66
	v_and_b32_e32 v85, 0xffff0000, v66
	v_lshlrev_b32_e32 v86, 16, v67
	v_and_b32_e32 v87, 0xffff0000, v67
	v_mul_f32_e32 v2, v2, v80
	v_mul_f32_e32 v3, v3, v81
	v_mul_f32_e32 v4, v4, v82
	v_mul_f32_e32 v5, v5, v83
	v_mul_f32_e32 v6, v6, v84
	v_mul_f32_e32 v7, v7, v85
	v_mul_f32_e32 v8, v8, v86
	v_mul_f32_e32 v9, v9, v87
	s_or_b64 exec, exec, s[8:9]
	s_and_saveexec_b64 s[8:9], s[6:7]
	v_add_u32_e32 v79, 0x14000, v78
	ds_write_b128 v79, v[2:5]
	ds_write_b128 v79, v[6:9] offset:16
	s_or_b64 exec, exec, s[8:9]
	.p2align	6

.LBB7_1426:
	s_cmp_lt_i32 s87, 31
	s_cselect_b64 s[0:1], -1, 0
	s_cmp_gt_i32 s89, 30
	s_cselect_b64 s[2:3], -1, 0
	s_and_b64 s[0:1], s[0:1], s[2:3]
	s_and_b64 vcc, exec, s[0:1]
	v_readlane_b32 s12, v251, 8
	v_readlane_b32 s13, v251, 9
	s_cbranch_vccz .LBB7_1432
	v_readlane_b32 s0, v251, 0
	v_readlane_b32 s1, v251, 1
	s_cmpk_gt_i32 s12, 0x7fff
	v_writelane_b32 v251, s0, 0
	s_nop 1
	v_writelane_b32 v251, s1, 1
	s_cbranch_scc1 .LBB7_1432
	v_readlane_b32 s0, v251, 0
	v_readlane_b32 s1, v251, 1
	s_load_dwordx4 s[4:7], s[0:1], 0x110
	s_load_dwordx2 s[2:3], s[0:1], 0x120
	s_waitcnt vmcnt(0)
	v_lshlrev_b32_e32 v20, 5, v201
	v_and_b32_e32 v16, 64, v163
	v_add_u32_e32 v16, 64, v16
	s_waitcnt lgkmcnt(0)
	global_load_dwordx4 v[0:3], v20, s[4:5] offset:16
	global_load_dwordx4 v[4:7], v20, s[4:5]
	global_load_dwordx4 v[8:11], v20, s[4:5] offset:2064
	global_load_dwordx4 v[12:15], v20, s[4:5] offset:2048
	v_xor_b32_e32 v17, 1, v163
	v_cmp_lt_i32_e32 vcc, v17, v16
	s_ashr_i32 s13, s12, 31
	s_lshl_b64 s[0:1], s[12:13], 6
	v_cndmask_b32_e32 v17, v163, v17, vcc
	v_lshlrev_b32_e32 v22, 2, v17
	v_xor_b32_e32 v17, 2, v163
	v_cmp_lt_i32_e32 vcc, v17, v16
	s_add_u32 s0, s2, s0
	v_readlane_b32 s14, v251, 6
	v_cndmask_b32_e32 v17, v163, v17, vcc
	v_lshlrev_b32_e32 v23, 2, v17
	v_xor_b32_e32 v17, 4, v163
	v_cmp_lt_i32_e32 vcc, v17, v16
	v_lshlrev_b32_e32 v28, 2, v201
	v_mov_b32_e32 v29, 0
	v_cndmask_b32_e32 v17, v163, v17, vcc
	v_lshlrev_b32_e32 v24, 2, v17
	v_xor_b32_e32 v17, 8, v163
	v_cmp_lt_i32_e32 vcc, v17, v16
	s_addc_u32 s1, s3, s1
	v_readlane_b32 s15, v251, 7
	v_cndmask_b32_e32 v17, v163, v17, vcc
	v_lshlrev_b32_e32 v25, 2, v17
	v_xor_b32_e32 v17, 16, v163
	v_cmp_lt_i32_e32 vcc, v17, v16
	s_ashr_i32 s15, s14, 31
	s_lshl_b64 s[4:5], s[12:13], 11
	v_cndmask_b32_e32 v17, v163, v17, vcc
	v_lshlrev_b32_e32 v26, 2, v17
	v_xor_b32_e32 v17, 32, v163
	v_cmp_lt_i32_e32 vcc, v17, v16
	v_mov_b32_e32 v21, v29
	v_readlane_b32 s16, v251, 4
	v_cndmask_b32_e32 v16, v163, v17, vcc
	v_lshlrev_b32_e32 v27, 2, v16
	v_lshl_add_u64 v[16:17], s[0:1], 0, v[28:29]
	s_mov_b64 s[0:1], 0x1ce80000
	v_lshl_add_u64 v[16:17], v[16:17], 0, s[0:1]
	s_lshl_b64 s[0:1], s[14:15], 6
	s_add_u32 s2, s2, s4
	v_lshlrev_b32_e32 v28, 4, v201
	s_addc_u32 s3, s3, s5
	v_lshl_add_u64 v[18:19], s[2:3], 0, v[28:29]
	s_mov_b64 s[2:3], 0xa380400
	v_lshl_add_u64 v[18:19], v[18:19], 0, s[2:3]
	s_lshl_b64 s[2:3], s[14:15], 11
	s_lshl_b64 s[4:5], s[12:13], 12
	s_add_u32 s4, s6, s4
	s_addc_u32 s5, s7, s5
	v_lshl_add_u64 v[20:21], s[4:5], 0, v[20:21]
	s_lshl_b64 s[4:5], s[14:15], 12
	v_mov_b32_e32 v28, 0x358637bd
	s_mov_b32 s8, 0x800000
	v_readlane_b32 s17, v251, 5
	v_mov_b32_e32 v29, 0
	s_and_saveexec_b64 s[6:7], s[16:17]
	global_load_dword v29, v[16:17], off
	s_or_b64 exec, exec, s[6:7]
	global_load_dwordx4 v[30:33], v[18:19], off offset:-1024
	global_load_dwordx4 v[34:37], v[18:19], off
	s_waitcnt vmcnt(0)
	s_branch .Lfn_body
	.p2align	6
